# layer-1 cache conversion split over the idle tails of layer 0's gemm2 phase (workgroups without an 11th tile) and out phase (workgroups without a third tile); hand-written streaming conversion, pre-ph
# baseline (speedup 1.0000x reference)
; DI int otid() { int t = __builtin_amdgcn_workitem_id_x(); asm volatile("" : "+v"(t)); return t; }
; DI void gbar(GBar& g) {
;   g.k++;
;   asm volatile("s_waitcnt vmcnt(0) lgkmcnt(0)" ::: "memory");
;   __syncthreads();
;   if (otid() == 0) {
;     const unsigned a = __hip_atomic_fetch_add(&g.w[1152 + 64 * g.xcc], 1u, __ATOMIC_RELAXED, __HIP_MEMORY_SCOPE_AGENT) + 1u;
;     if (a == g.k * g.mycen) {
;       __builtin_amdgcn_fence(__ATOMIC_RELEASE, "agent");
;       asm volatile("s_waitcnt vmcnt(0)" ::: "memory");
;       __hip_atomic_fetch_add(&g.w[2240], 1u, __ATOMIC_RELAXED, __HIP_MEMORY_SCOPE_AGENT);
;     }
; DI void convert_caches(const Params& p, int l) {
;   const int tid = otid();
;   const long total = (long)32 * 2048 * 40;
;   for (long e = (long)blockIdx.x * 256 + tid; e < total; e += (long)gridDim.x * 256) {
;     const int row = (int)(e / 40), c = (int)(e - (long)row * 40);
;     const int b = row >> 11, pos = row & 2047;
;     const size_t drow = (size_t)16384 + (size_t)b * 2112 + pos;
;     const size_t srow = (size_t)(l * 32 + b) * 2048 + pos;
;     if (c < 16) *(bf16x8*)(p.KB + drow * 128 + c * 8) = cvt8(p.cache_k + srow * 128 + c * 8);
;     else if (c < 32) *(bf16x8*)(p.VB + drow * 128 + (c - 16) * 8) = cvt8(p.cache_v + srow * 128 + (c - 16) * 8);
;     else *(bf16x8*)(p.KIB + drow * 64 + (c - 32) * 8) = cvt8(p.cache_kidx + srow * 64 + (c - 32) * 8);
;   }
; }
.LBB0_1706:
	v_readlane_b32 s4, v254, 51
	v_readlane_b32 s98, v254, 0
	s_nop 1
	s_cmp_lg_u32 s4, 0
	s_cbranch_scc1 .Lcv_skipa
	s_cmp_lt_u32 s98, 64
	s_cbranch_scc1 .Lcv_skipa
	s_load_dwordx2 s[4:5], s[0:1], 0x18
	s_load_dwordx2 s[6:7], s[0:1], 0x20
	s_load_dwordx2 s[8:9], s[0:1], 0x28
	s_load_dwordx2 s[10:11], s[0:1], 0x168
	s_load_dwordx2 s[12:13], s[0:1], 0x170
	s_load_dwordx2 s[14:15], s[0:1], 0x178
	v_lshrrev_b32_e32 v4, 6, v182
	v_and_b32_e32 v5, 63, v182
	s_nop 0
	v_readfirstlane_b32 s99, v4
	v_lshrrev_b32_e32 v40, 4, v5
	v_and_b32_e32 v41, 15, v5
	s_sub_u32 s98, s98, 64
	s_lshl_b32 s98, s98, 2
	s_add_u32 s98, s98, s99
	s_add_u32 s98, s98, 0x0
	s_waitcnt lgkmcnt(0)
	s_add_u32 s4, s4, 0x2000000
	s_addc_u32 s5, s5, 0
	s_add_u32 s6, s6, 0x2000000
	s_addc_u32 s7, s7, 0
	s_add_u32 s8, s8, 0x1000000
	s_addc_u32 s9, s9, 0
.Lcv_loopa:
	s_lshl_b32 s101, s98, 2
	v_add_u32_e32 v42, s101, v40
	v_lshlrev_b32_e32 v43, 9, v42
	v_lshl_add_u32 v43, v41, 5, v43
	v_lshlrev_b32_e32 v44, 8, v42
	v_lshl_add_u32 v44, v41, 4, v44
	v_lshrrev_b32_e32 v45, 11, v42
	v_lshl_add_u32 v45, v45, 6, v42
	v_add_u32_e32 v45, 0x4000, v45
	v_lshlrev_b32_e32 v46, 8, v45
	v_lshl_add_u32 v46, v41, 4, v46
	v_lshlrev_b32_e32 v47, 7, v45
	v_lshl_add_u32 v47, v41, 3, v47
	global_load_dwordx4 v[48:51], v43, s[4:5]
	global_load_dwordx4 v[52:55], v43, s[4:5] offset:16
	global_load_dwordx4 v[56:59], v43, s[6:7]
	global_load_dwordx4 v[60:63], v43, s[6:7] offset:16
	global_load_dwordx4 v[64:67], v44, s[8:9]
	s_add_u32 s100, s98, 0x700
	s_cmp_lt_u32 s100, 0x2000
	s_cbranch_scc0 .Lcv_onea
	s_lshl_b32 s101, s100, 2
	v_add_u32_e32 v68, s101, v40
	v_lshlrev_b32_e32 v69, 9, v68
	v_lshl_add_u32 v69, v41, 5, v69
	v_lshlrev_b32_e32 v70, 8, v68
	v_lshl_add_u32 v70, v41, 4, v70
	v_lshrrev_b32_e32 v71, 11, v68
	v_lshl_add_u32 v71, v71, 6, v68
	v_add_u32_e32 v71, 0x4000, v71
	v_lshlrev_b32_e32 v72, 8, v71
	v_lshl_add_u32 v72, v41, 4, v72
	v_lshlrev_b32_e32 v73, 7, v71
	v_lshl_add_u32 v73, v41, 3, v73
	global_load_dwordx4 v[74:77], v69, s[4:5]
	global_load_dwordx4 v[78:81], v69, s[4:5] offset:16
	global_load_dwordx4 v[82:85], v69, s[6:7]
	global_load_dwordx4 v[86:89], v69, s[6:7] offset:16
	global_load_dwordx4 v[90:93], v70, s[8:9]
	s_waitcnt vmcnt(5)
	v_cvt_pk_bf16_f32 v48, v48, v49
	v_cvt_pk_bf16_f32 v49, v50, v51
	v_cvt_pk_bf16_f32 v50, v52, v53
	v_cvt_pk_bf16_f32 v51, v54, v55
	v_cvt_pk_bf16_f32 v56, v56, v57
	v_cvt_pk_bf16_f32 v57, v58, v59
	v_cvt_pk_bf16_f32 v58, v60, v61
	v_cvt_pk_bf16_f32 v59, v62, v63
	v_cvt_pk_bf16_f32 v64, v64, v65
	v_cvt_pk_bf16_f32 v65, v66, v67
	global_store_dwordx4 v46, v[48:51], s[10:11]
	global_store_dwordx4 v46, v[56:59], s[12:13]
	global_store_dwordx2 v47, v[64:65], s[14:15]
	s_waitcnt vmcnt(3)
	v_cvt_pk_bf16_f32 v74, v74, v75
	v_cvt_pk_bf16_f32 v75, v76, v77
	v_cvt_pk_bf16_f32 v76, v78, v79
	v_cvt_pk_bf16_f32 v77, v80, v81
	v_cvt_pk_bf16_f32 v82, v82, v83
	v_cvt_pk_bf16_f32 v83, v84, v85
	v_cvt_pk_bf16_f32 v84, v86, v87
	v_cvt_pk_bf16_f32 v85, v88, v89
	v_cvt_pk_bf16_f32 v90, v90, v91
	v_cvt_pk_bf16_f32 v91, v92, v93
	global_store_dwordx4 v72, v[74:77], s[10:11]
	global_store_dwordx4 v72, v[82:85], s[12:13]
	global_store_dwordx2 v73, v[90:91], s[14:15]
	s_add_u32 s98, s98, 0xe00
	s_cmp_lt_u32 s98, 0x2000
	s_cbranch_scc1 .Lcv_loopa
	s_branch .Lcv_skipa
.Lcv_onea:
	s_waitcnt vmcnt(0)
	v_cvt_pk_bf16_f32 v48, v48, v49
	v_cvt_pk_bf16_f32 v49, v50, v51
	v_cvt_pk_bf16_f32 v50, v52, v53
	v_cvt_pk_bf16_f32 v51, v54, v55
	v_cvt_pk_bf16_f32 v56, v56, v57
	v_cvt_pk_bf16_f32 v57, v58, v59
	v_cvt_pk_bf16_f32 v58, v60, v61
	v_cvt_pk_bf16_f32 v59, v62, v63
	v_cvt_pk_bf16_f32 v64, v64, v65
	v_cvt_pk_bf16_f32 v65, v66, v67
	global_store_dwordx4 v46, v[48:51], s[10:11]
	global_store_dwordx4 v46, v[56:59], s[12:13]
	global_store_dwordx2 v47, v[64:65], s[14:15]
.Lcv_skipa:
	s_waitcnt vmcnt(0) lgkmcnt(0)
	v_mov_b32_e32 v4, v182
	s_waitcnt vmcnt(63) expcnt(7) lgkmcnt(15)
	s_barrier
	s_nop 0
	v_cmp_eq_u32_e32 vcc, 0, v4
	s_and_saveexec_b64 s[4:5], vcc
	s_cbranch_execz .LBB0_1715
	s_mov_b64 s[8:9], exec
	v_mbcnt_lo_u32_b32 v4, s8, 0
	v_mbcnt_hi_u32_b32 v4, s9, v4
	v_cmp_eq_u32_e32 vcc, 0, v4
	s_and_saveexec_b64 s[6:7], vcc
	s_cbranch_execz .LBB0_1709
	s_bcnt1_i32_b64 s8, s[8:9]
	v_mov_b32_e32 v5, s8
	v_readlane_b32 s8, v254, 14
	v_readlane_b32 s9, v254, 15
	s_nop 4
	global_atomic_add v5, v164, v5, s[8:9] sc0

; DI int otid() { int t = __builtin_amdgcn_workitem_id_x(); asm volatile("" : "+v"(t)); return t; }
; DI void convert_caches(const Params& p, int l) {
;   const int tid = otid();
;   const long total = (long)32 * 2048 * 40;
;   for (long e = (long)blockIdx.x * 256 + tid; e < total; e += (long)gridDim.x * 256) {
;     const int row = (int)(e / 40), c = (int)(e - (long)row * 40);
;     const int b = row >> 11, pos = row & 2047;
;     const size_t drow = (size_t)16384 + (size_t)b * 2112 + pos;
;     const size_t srow = (size_t)(l * 32 + b) * 2048 + pos;
;     if (c < 16) *(bf16x8*)(p.KB + drow * 128 + c * 8) = cvt8(p.cache_k + srow * 128 + c * 8);
;     else if (c < 32) *(bf16x8*)(p.VB + drow * 128 + (c - 16) * 8) = cvt8(p.cache_v + srow * 128 + (c - 16) * 8);
;     else *(bf16x8*)(p.KIB + drow * 64 + (c - 32) * 8) = cvt8(p.cache_kidx + srow * 64 + (c - 32) * 8);
;   }
; }
.LBB0_1867:
	v_readlane_b32 s4, v254, 51
	v_readlane_b32 s98, v254, 0
	s_nop 1
	s_cmp_lg_u32 s4, 0
	s_cbranch_scc1 .Lcv_skipb
	s_cmp_lt_u32 s98, 128
	s_cbranch_scc1 .Lcv_skipb
	s_load_dwordx2 s[4:5], s[0:1], 0x18
	s_load_dwordx2 s[6:7], s[0:1], 0x20
	s_load_dwordx2 s[8:9], s[0:1], 0x28
	s_load_dwordx2 s[10:11], s[0:1], 0x168
	s_load_dwordx2 s[12:13], s[0:1], 0x170
	s_load_dwordx2 s[14:15], s[0:1], 0x178
	v_lshrrev_b32_e32 v4, 6, v182
	v_and_b32_e32 v5, 63, v182
	s_nop 0
	v_readfirstlane_b32 s99, v4
	v_lshrrev_b32_e32 v40, 4, v5
	v_and_b32_e32 v41, 15, v5
	s_sub_u32 s98, s98, 128
	s_lshl_b32 s98, s98, 2
	s_add_u32 s98, s98, s99
	s_add_u32 s98, s98, 0x2000
	s_waitcnt lgkmcnt(0)
	s_add_u32 s4, s4, 0x2000000
	s_addc_u32 s5, s5, 0
	s_add_u32 s6, s6, 0x2000000
	s_addc_u32 s7, s7, 0
	s_add_u32 s8, s8, 0x1000000
	s_addc_u32 s9, s9, 0
